# DK32 attention: stream-0 max subtraction folded into QK MFMA C operand (first tile peeled), K-frag registers shared by both streams
# speedup vs baseline: 1.0255x; 1.0117x over previous
; template <int DK>
; DI void attn_item(const Params& p, int layer, int b, int hd, int qt, int ctxq, char* smem) {
;     ...
;     for (int kt = 0; kt < nkt; ++kt) {
;         const int cur = kt & 1;
;         const bf16_t* kb_ = sK + cur * 64 * 72; const bf16_t* vb_ = sV + cur * 64 * 68;
; #pragma unroll
;         for (int s = 0; s < 2; ++s) {
;             if (s == 1) {
;                 if (kt + 1 < nkt) {
; #pragma unroll
;                     for (int i = 0; i < 2; ++i) { rk[i] = *(const u32x4*)(Kg + (size_t)((kt + 1) * 64 + srow + 32 * i) * 64 + sc8); rv[i] = *(const u32x4*)(Vg + (size_t)(srow + 32 * i) * NKEY + (kt + 1) * 64 + sc8); }
;                 }
;             }
;             f32x16 x[2];
; #pragma unroll
;             for (int kb = 0; kb < 2; ++kb)
; #pragma unroll
;                 for (int i = 0; i < 16; ++i) x[kb][i] = 0.f;
;             const int kofs = DK == 32 ? 32 * s : 0;
; #pragma unroll
;             for (int ks = 0; ks < NKS; ++ks) {
;                 const bf16x8 a0 = *(const bf16x8*)(kb_ + r * 72 + kofs + 16 * ks + 8 * h), a1 = *(const bf16x8*)(kb_ + (32 + r) * 72 + kofs + 16 * ks + 8 * h);
;                 const bf16x8 qv = *(const bf16x8*)(sQ + ((s * NKS + ks) * 64 + lane) * 8);
;                 x[0] = MFMA32(a0, qv, x[0]); x[1] = MFMA32(a1, qv, x[1]);
;             }
;             float mx = x[0][0];
; #pragma unroll
;             for (int i = 1; i < 16; ++i) mx = fmaxf(mx, x[0][i]);
; #pragma unroll
;             for (int i = 0; i < 16; ++i) mx = fmaxf(mx, x[1][i]);
;             mx = fmaxf(mx, shx(mx, lane, 32));
;             if (__builtin_amdgcn_ballot_w64(mx > m_[s] + 8.f) != 0) {
;                 const float mn = fmaxf(m_[s], mx);
;                 const float al = __builtin_amdgcn_exp2f(m_[s] - mn);
;                 m_[s] = mn;
;                 l_[s] *= al;
; #pragma unroll
;                 for (int d = 0; d < 2; ++d)
; #pragma unroll
;                     for (int i = 0; i < 16; ++i) O[s][d][i] *= al;
;             }
;             const f32x2 mref = {m_[s], m_[s]};
;             float ps = 0.f;
; #pragma unroll
;             for (int kb = 0; kb < 2; ++kb)
; #pragma unroll
;                 for (int i2 = 0; i2 < 8; ++i2) {
;                     f32x2 t = {x[kb][2 * i2], x[kb][2 * i2 + 1]};
;                     asm("v_pk_add_f32 %0, %1, %2 neg_lo:[0,1] neg_hi:[0,1]" : "=v"(t) : "v"(t), "v"(mref));
.LBB0_158:
	s_mov_b32 s8, 0
	ds_read_b128 v[216:219], v171 offset:35840
	ds_read_b128 v[220:223], v171 offset:36864
	ds_read_b128 v[224:227], v171 offset:37888
	ds_read_b128 v[240:243], v171 offset:38912
	ds_read_b128 v[128:131], v149
	ds_read_b128 v[132:135], v149 offset:4608
	ds_read_b128 v[136:139], v149 offset:32
	ds_read_b128 v[140:143], v149 offset:4640
	v_lshl_add_u64 v[244:245], v[154:155], 0, v[160:161]
	s_mov_b64 s[10:11], 0x84000
	v_lshl_add_u64 v[246:247], v[244:245], 0, s[10:11]
	v_lshl_add_u64 v[248:249], v[156:157], 0, v[160:161]
	s_mov_b64 s[10:11], 0x3000
	v_lshl_add_u64 v[248:249], v[248:249], 0, s[10:11]
	global_load_dwordx4 v[190:193], v[248:249], off offset:-4096
	global_load_dwordx4 v[194:197], v[248:249], off
	global_load_dwordx4 v[198:201], v[244:245], off offset:128
	global_load_dwordx4 v[202:205], v[246:247], off offset:128
	v_mov_b32_e32 v153, v152
	v_mov_b32_e32 v147, v146
	s_and_b32 s9, s8, 1
	s_mul_i32 s10, s9, 0x2400
	s_mul_i32 s11, s9, 0x2200
	v_add_u32_e32 v206, s10, v149
	v_add_u32_e32 v207, s11, v172
	v_add_u32_e32 v208, 0x5800, v207
	v_add_u32_e32 v207, 0x4800, v207
	s_waitcnt lgkmcnt(0)
	v_mfma_f32_32x32x16_bf16 v[80:95], v[128:131], v[216:219], 0
	v_mfma_f32_32x32x16_bf16 v[80:95], v[136:139], v[220:223], v[80:95]
	v_mfma_f32_32x32x16_bf16 v[64:79], v[132:135], v[216:219], 0
	v_mfma_f32_32x32x16_bf16 v[64:79], v[140:143], v[220:223], v[64:79]
	ds_read2_b64 v[96:99], v207 offset0:0 offset1:2
	ds_read2_b64 v[112:115], v208 offset0:32 offset1:34
	ds_read2_b64 v[100:103], v207 offset0:4 offset1:6
	ds_read2_b64 v[116:119], v208 offset0:36 offset1:38
	ds_read2_b64 v[104:107], v207 offset0:8 offset1:10
	ds_read2_b64 v[120:123], v208 offset0:40 offset1:42
	ds_read2_b64 v[108:111], v207 offset0:12 offset1:14
	ds_read2_b64 v[124:127], v208 offset0:44 offset1:46
	ds_read_b128 v[128:131], v206 offset:64
	ds_read_b128 v[132:135], v206 offset:4672
	ds_read_b128 v[136:139], v206 offset:96
	ds_read_b128 v[140:143], v206 offset:4704
	v_max3_f32 v209, v80, v81, v82
	v_max3_f32 v209, v209, v83, v84
	v_max3_f32 v209, v209, v85, v86
	v_max3_f32 v209, v209, v87, v88
	v_max3_f32 v209, v209, v89, v90
	v_max3_f32 v209, v209, v91, v92
	v_max3_f32 v209, v209, v93, v94
	v_max3_f32 v209, v209, v95, v64
	v_max3_f32 v209, v209, v65, v66
	v_max3_f32 v209, v209, v67, v68
	v_max3_f32 v209, v209, v69, v70
	v_max3_f32 v209, v209, v71, v72
	v_max3_f32 v209, v209, v73, v74
	v_max3_f32 v209, v209, v75, v76
	v_max3_f32 v209, v209, v77, v78
	v_max_f32_e32 v209, v209, v79
	v_mov_b32_e32 v210, v209
	s_nop 1
	v_permlane32_swap_b32_e32 v210, v209
	s_nop 0
	v_max_f32_e32 v209, v209, v210
	v_add_f32_e32 v210, 0x41000000, v152
	v_cmp_gt_f32_e32 vcc, v209, v210
	s_cbranch_vccz .Lat32_nors0f
	v_max_f32_e32 v213, v152, v209
	v_sub_f32_e32 v210, v152, v213
	v_exp_f32_e32 v210, v210
	v_mov_b32_e32 v152, v213
	v_mov_b32_e32 v153, v213
	v_mul_f32_e32 v151, v151, v210
	v_pk_mul_f32 v[32:33], v[32:33], v[210:211] op_sel_hi:[1,0]
	v_pk_mul_f32 v[34:35], v[34:35], v[210:211] op_sel_hi:[1,0]
	v_pk_mul_f32 v[36:37], v[36:37], v[210:211] op_sel_hi:[1,0]
	v_pk_mul_f32 v[38:39], v[38:39], v[210:211] op_sel_hi:[1,0]
	v_pk_mul_f32 v[40:41], v[40:41], v[210:211] op_sel_hi:[1,0]
	v_pk_mul_f32 v[42:43], v[42:43], v[210:211] op_sel_hi:[1,0]
	v_pk_mul_f32 v[44:45], v[44:45], v[210:211] op_sel_hi:[1,0]
	v_pk_mul_f32 v[46:47], v[46:47], v[210:211] op_sel_hi:[1,0]
	v_pk_mul_f32 v[0:1], v[0:1], v[210:211] op_sel_hi:[1,0]
	v_pk_mul_f32 v[2:3], v[2:3], v[210:211] op_sel_hi:[1,0]
	v_pk_mul_f32 v[4:5], v[4:5], v[210:211] op_sel_hi:[1,0]
	v_pk_mul_f32 v[6:7], v[6:7], v[210:211] op_sel_hi:[1,0]
	v_pk_mul_f32 v[8:9], v[8:9], v[210:211] op_sel_hi:[1,0]
	v_pk_mul_f32 v[10:11], v[10:11], v[210:211] op_sel_hi:[1,0]
	v_pk_mul_f32 v[12:13], v[12:13], v[210:211] op_sel_hi:[1,0]
	v_pk_mul_f32 v[14:15], v[14:15], v[210:211] op_sel_hi:[1,0]
.Lat32_nors0f:
	v_pk_add_f32 v[80:81], v[80:81], v[152:153] neg_lo:[0,1] neg_hi:[0,1]
	v_pk_add_f32 v[82:83], v[82:83], v[152:153] neg_lo:[0,1] neg_hi:[0,1]
	v_pk_add_f32 v[84:85], v[84:85], v[152:153] neg_lo:[0,1] neg_hi:[0,1]
	v_pk_add_f32 v[86:87], v[86:87], v[152:153] neg_lo:[0,1] neg_hi:[0,1]
	v_exp_f32_e32 v80, v80
	v_exp_f32_e32 v81, v81
	v_exp_f32_e32 v82, v82
	v_exp_f32_e32 v83, v83
	v_exp_f32_e32 v84, v84
	v_exp_f32_e32 v85, v85
	v_exp_f32_e32 v86, v86
	v_exp_f32_e32 v87, v87
	v_add_f32_e32 v211, v80, v82
	v_add_f32_e32 v212, v81, v83
	v_add_f32_e32 v211, v211, v84
	v_add_f32_e32 v212, v212, v85
	v_add_f32_e32 v211, v211, v86
	v_add_f32_e32 v212, v212, v87
	v_cvt_pk_bf16_f32 v80, v80, v81
	v_cvt_pk_bf16_f32 v81, v82, v83
	v_cvt_pk_bf16_f32 v82, v84, v85
	v_cvt_pk_bf16_f32 v83, v86, v87
	s_waitcnt lgkmcnt(0)
; template <int DK>
; DI void attn_item(const Params& p, int layer, int b, int hd, int qt, int ctxq, char* smem) {
;     ...
;             float mx = x[0][0];
; #pragma unroll
;             for (int i = 1; i < 16; ++i) mx = fmaxf(mx, x[0][i]);
; #pragma unroll
;             for (int i = 0; i < 16; ++i) mx = fmaxf(mx, x[1][i]);
;             mx = fmaxf(mx, shx(mx, lane, 32));
;             if (__builtin_amdgcn_ballot_w64(mx > m_[s] + 8.f) != 0) {
;                 const float mn = fmaxf(m_[s], mx);
;                 const float al = __builtin_amdgcn_exp2f(m_[s] - mn);
;                 m_[s] = mn;
;                 l_[s] *= al;
; #pragma unroll
;                 for (int d = 0; d < 2; ++d)
; #pragma unroll
;                     for (int i = 0; i < 16; ++i) O[s][d][i] *= al;
;             }
;             const f32x2 mref = {m_[s], m_[s]};
;             float ps = 0.f;
; #pragma unroll
;             for (int kb = 0; kb < 2; ++kb)
; #pragma unroll
;                 for (int i2 = 0; i2 < 8; ++i2) {
;                     f32x2 t = {x[kb][2 * i2], x[kb][2 * i2 + 1]};
;                     asm("v_pk_add_f32 %0, %1, %2 neg_lo:[0,1] neg_hi:[0,1]" : "=v"(t) : "v"(t), "v"(mref));
;                     const float e0 = __builtin_amdgcn_exp2f(t.x), e1 = __builtin_amdgcn_exp2f(t.y);
;                     x[kb][2 * i2] = e0; x[kb][2 * i2 + 1] = e1; ps += e0 + e1;
;                 }
;             l_[s] += ps;
; #pragma unroll
;             for (int kb = 0; kb < 2; ++kb)
; #pragma unroll
;                 for (int st = 0; st < 2; ++st) {
;                     u32x4 w;
;                     w.x = pk_bf16(x[kb][8 * st], x[kb][8 * st + 1]); w.y = pk_bf16(x[kb][8 * st + 2], x[kb][8 * st + 3]);
;                     w.z = pk_bf16(x[kb][8 * st + 4], x[kb][8 * st + 5]); w.w = pk_bf16(x[kb][8 * st + 6], x[kb][8 * st + 7]);
;                     const bf16x8 pfr = __builtin_bit_cast(bf16x8, w);
; #pragma unroll
;                     for (int d = 0; d < 2; ++d) {
;                         const bf16_t* vp = vb_ + (32 * d + r) * 68 + 32 * kb + 16 * st + 4 * h;
;                         const s16x4 lo = *(const s16x4*)vp, hi = *(const s16x4*)(vp + 8);
;                         const bf16x8 vf = __builtin_shufflevector(lo, hi, 0, 1, 2, 3, 4, 5, 6, 7);
;                         O[s][d] = MFMA32(vf, pfr, O[s][d]);
;                     }
;                 }
;         }
;         if (kt + 1 < nkt) {
	v_pk_add_f32 v[88:89], v[88:89], v[152:153] neg_lo:[0,1] neg_hi:[0,1]
	v_pk_add_f32 v[90:91], v[90:91], v[152:153] neg_lo:[0,1] neg_hi:[0,1]
	v_pk_add_f32 v[92:93], v[92:93], v[152:153] neg_lo:[0,1] neg_hi:[0,1]
	v_pk_add_f32 v[94:95], v[94:95], v[152:153] neg_lo:[0,1] neg_hi:[0,1]
	v_mfma_f32_32x32x16_bf16 v[32:47], v[96:99], v[80:83], v[32:47]
	v_mfma_f32_32x32x16_bf16 v[0:15], v[112:115], v[80:83], v[0:15]
	v_exp_f32_e32 v88, v88
	v_exp_f32_e32 v89, v89
	v_exp_f32_e32 v90, v90
	v_exp_f32_e32 v91, v91
	v_exp_f32_e32 v92, v92
	v_exp_f32_e32 v93, v93
	v_exp_f32_e32 v94, v94
	v_exp_f32_e32 v95, v95
	v_add_f32_e32 v211, v211, v88
	v_add_f32_e32 v212, v212, v89
	v_add_f32_e32 v211, v211, v90
	v_add_f32_e32 v212, v212, v91
	v_add_f32_e32 v211, v211, v92
	v_add_f32_e32 v212, v212, v93
	v_add_f32_e32 v211, v211, v94
	v_add_f32_e32 v212, v212, v95
	v_cvt_pk_bf16_f32 v88, v88, v89
	v_cvt_pk_bf16_f32 v89, v90, v91
	v_cvt_pk_bf16_f32 v90, v92, v93
	v_cvt_pk_bf16_f32 v91, v94, v95
	v_pk_add_f32 v[64:65], v[64:65], v[152:153] neg_lo:[0,1] neg_hi:[0,1]
	v_pk_add_f32 v[66:67], v[66:67], v[152:153] neg_lo:[0,1] neg_hi:[0,1]
	v_pk_add_f32 v[68:69], v[68:69], v[152:153] neg_lo:[0,1] neg_hi:[0,1]
	v_pk_add_f32 v[70:71], v[70:71], v[152:153] neg_lo:[0,1] neg_hi:[0,1]
	v_mfma_f32_32x32x16_bf16 v[32:47], v[100:103], v[88:91], v[32:47]
	v_mfma_f32_32x32x16_bf16 v[0:15], v[116:119], v[88:91], v[0:15]
	v_mfma_f32_32x32x16_bf16 v[80:95], v[128:131], v[224:227], 0
	v_mfma_f32_32x32x16_bf16 v[80:95], v[136:139], v[240:243], v[80:95]
	v_exp_f32_e32 v64, v64
	v_exp_f32_e32 v65, v65
	v_exp_f32_e32 v66, v66
	v_exp_f32_e32 v67, v67
	v_exp_f32_e32 v68, v68
	v_exp_f32_e32 v69, v69
	v_exp_f32_e32 v70, v70
	v_exp_f32_e32 v71, v71
	v_add_f32_e32 v211, v211, v64
	v_add_f32_e32 v212, v212, v65
	v_add_f32_e32 v211, v211, v66
	v_add_f32_e32 v212, v212, v67
	v_add_f32_e32 v211, v211, v68
	v_add_f32_e32 v212, v212, v69
	v_add_f32_e32 v211, v211, v70
	v_add_f32_e32 v212, v212, v71
	v_cvt_pk_bf16_f32 v64, v64, v65
	v_cvt_pk_bf16_f32 v65, v66, v67
	v_cvt_pk_bf16_f32 v66, v68, v69
	v_cvt_pk_bf16_f32 v67, v70, v71
	v_pk_add_f32 v[72:73], v[72:73], v[152:153] neg_lo:[0,1] neg_hi:[0,1]
	v_pk_add_f32 v[74:75], v[74:75], v[152:153] neg_lo:[0,1] neg_hi:[0,1]
	v_pk_add_f32 v[76:77], v[76:77], v[152:153] neg_lo:[0,1] neg_hi:[0,1]
	v_pk_add_f32 v[78:79], v[78:79], v[152:153] neg_lo:[0,1] neg_hi:[0,1]
	v_mfma_f32_32x32x16_bf16 v[32:47], v[104:107], v[64:67], v[32:47]
	v_mfma_f32_32x32x16_bf16 v[0:15], v[120:123], v[64:67], v[0:15]
	v_exp_f32_e32 v72, v72
	v_exp_f32_e32 v73, v73
	v_exp_f32_e32 v74, v74
	v_exp_f32_e32 v75, v75
	v_exp_f32_e32 v76, v76
	v_exp_f32_e32 v77, v77
	v_exp_f32_e32 v78, v78
	v_exp_f32_e32 v79, v79
	v_add_f32_e32 v211, v211, v72
	v_add_f32_e32 v212, v212, v73
	v_add_f32_e32 v211, v211, v74
	v_add_f32_e32 v212, v212, v75
	v_add_f32_e32 v211, v211, v76
	v_add_f32_e32 v212, v212, v77
	v_add_f32_e32 v211, v211, v78
	v_add_f32_e32 v212, v212, v79
	v_cvt_pk_bf16_f32 v72, v72, v73
	v_cvt_pk_bf16_f32 v73, v74, v75
	v_cvt_pk_bf16_f32 v74, v76, v77
	v_cvt_pk_bf16_f32 v75, v78, v79
	v_add_f32_e32 v211, v211, v212
	v_add_f32_e32 v151, v151, v211
	v_mfma_f32_32x32x16_bf16 v[32:47], v[108:111], v[72:75], v[32:47]
	v_mfma_f32_32x32x16_bf16 v[0:15], v[124:127], v[72:75], v[0:15]
	v_mfma_f32_32x32x16_bf16 v[64:79], v[132:135], v[224:227], 0
	v_mfma_f32_32x32x16_bf16 v[64:79], v[140:143], v[240:243], v[64:79]
	v_sub_f32_e32 v174, 0, v152
	v_sub_f32_e32 v175, 0, v152
	v_sub_f32_e32 v176, 0, v152
	v_sub_f32_e32 v177, 0, v152
	v_sub_f32_e32 v178, 0, v152
	v_sub_f32_e32 v179, 0, v152
	v_sub_f32_e32 v180, 0, v152
	v_sub_f32_e32 v181, 0, v152
	v_sub_f32_e32 v182, 0, v152
	v_sub_f32_e32 v183, 0, v152
	v_sub_f32_e32 v184, 0, v152
	v_sub_f32_e32 v185, 0, v152
	v_sub_f32_e32 v186, 0, v152
	v_sub_f32_e32 v187, 0, v152
	v_sub_f32_e32 v188, 0, v152
	v_sub_f32_e32 v189, 0, v152
	s_xor_b32 s9, s9, 1
	s_mul_i32 s10, s9, 0x2400
	s_mul_i32 s11, s9, 0x2200
	v_add_u32_e32 v214, s10, v148
	v_add_u32_e32 v215, s11, v150
	v_add_u32_e32 v213, 0x5900, v215
	v_add_u32_e32 v215, 0x4800, v215
	v_add_u32_e32 v206, s10, v149
	s_waitcnt vmcnt(0)
	ds_write_b128 v214, v[190:193]
	ds_write_b128 v214, v[194:197] offset:4608
	ds_write2_b64 v215, v[198:199], v[200:201] offset1:1
	ds_write2_b64 v213, v[202:203], v[204:205] offset1:1
	s_mov_b64 s[10:11], 0x80
	v_lshl_add_u64 v[244:245], v[244:245], 0, s[10:11]
	v_lshl_add_u64 v[246:247], v[246:247], 0, s[10:11]
	s_mov_b64 s[10:11], 0x2000
	v_lshl_add_u64 v[248:249], v[248:249], 0, s[10:11]
	global_load_dwordx4 v[190:193], v[248:249], off offset:-4096
	global_load_dwordx4 v[194:197], v[248:249], off
	global_load_dwordx4 v[198:201], v[244:245], off offset:128
	global_load_dwordx4 v[202:205], v[246:247], off offset:128
	v_max3_f32 v209, v80, v81, v82
	v_max3_f32 v209, v209, v83, v84
	v_max3_f32 v209, v209, v85, v86
	v_max3_f32 v209, v209, v87, v88
	v_max3_f32 v209, v209, v89, v90
	v_max3_f32 v209, v209, v91, v92
	v_max3_f32 v209, v209, v93, v94
	v_max3_f32 v209, v209, v95, v64
	v_max3_f32 v209, v209, v65, v66
	v_max3_f32 v209, v209, v67, v68
	v_max3_f32 v209, v209, v69, v70
	v_max3_f32 v209, v209, v71, v72
	v_max3_f32 v209, v209, v73, v74
	v_max3_f32 v209, v209, v75, v76
	v_max3_f32 v209, v209, v77, v78
	v_max_f32_e32 v209, v209, v79
	v_mov_b32_e32 v210, v209
	s_nop 1
	v_permlane32_swap_b32_e32 v210, v209
	s_nop 0
	v_max_f32_e32 v209, v209, v210
	v_add_f32_e32 v210, 0x41000000, v146
	v_cmp_gt_f32_e32 vcc, v209, v210
	s_cbranch_vccz .Lat32_nors1f
	v_max_f32_e32 v213, v146, v209
	v_sub_f32_e32 v210, v146, v213
	v_exp_f32_e32 v210, v210
	v_mov_b32_e32 v146, v213
	v_mov_b32_e32 v147, v213
	v_mul_f32_e32 v170, v170, v210
	v_pk_mul_f32 v[48:49], v[48:49], v[210:211] op_sel_hi:[1,0]
	v_pk_mul_f32 v[50:51], v[50:51], v[210:211] op_sel_hi:[1,0]
	v_pk_mul_f32 v[52:53], v[52:53], v[210:211] op_sel_hi:[1,0]
	v_pk_mul_f32 v[54:55], v[54:55], v[210:211] op_sel_hi:[1,0]
	v_pk_mul_f32 v[56:57], v[56:57], v[210:211] op_sel_hi:[1,0]
	v_pk_mul_f32 v[58:59], v[58:59], v[210:211] op_sel_hi:[1,0]
	v_pk_mul_f32 v[60:61], v[60:61], v[210:211] op_sel_hi:[1,0]
	v_pk_mul_f32 v[62:63], v[62:63], v[210:211] op_sel_hi:[1,0]
	v_pk_mul_f32 v[16:17], v[16:17], v[210:211] op_sel_hi:[1,0]
	v_pk_mul_f32 v[18:19], v[18:19], v[210:211] op_sel_hi:[1,0]
	v_pk_mul_f32 v[20:21], v[20:21], v[210:211] op_sel_hi:[1,0]
	v_pk_mul_f32 v[22:23], v[22:23], v[210:211] op_sel_hi:[1,0]
	v_pk_mul_f32 v[24:25], v[24:25], v[210:211] op_sel_hi:[1,0]
	v_pk_mul_f32 v[26:27], v[26:27], v[210:211] op_sel_hi:[1,0]
	v_pk_mul_f32 v[28:29], v[28:29], v[210:211] op_sel_hi:[1,0]
	v_pk_mul_f32 v[30:31], v[30:31], v[210:211] op_sel_hi:[1,0]

; #define MFMA32(a, b, c) __builtin_amdgcn_mfma_f32_32x32x16_bf16((a), (b), (c), 0, 0, 0)
; DI float shx(float v, int lane, int m) { return __int_as_float(__builtin_amdgcn_ds_bpermute((lane ^ m) << 2, __float_as_int(v))); }
; template <int DK>
; DI void attn_item(const Params& p, int layer, int b, int hd, int qt, int ctxq, char* smem) {
;     ...
;             f32x16 x[2];
; #pragma unroll
;             for (int kb = 0; kb < 2; ++kb)
; #pragma unroll
;                 for (int i = 0; i < 16; ++i) x[kb][i] = 0.f;
;             const int kofs = DK == 32 ? 32 * s : 0;
; #pragma unroll
;             for (int ks = 0; ks < NKS; ++ks) {
;                 const bf16x8 a0 = *(const bf16x8*)(kb_ + r * 72 + kofs + 16 * ks + 8 * h), a1 = *(const bf16x8*)(kb_ + (32 + r) * 72 + kofs + 16 * ks + 8 * h);
;                 const bf16x8 qv = *(const bf16x8*)(sQ + ((s * NKS + ks) * 64 + lane) * 8);
;                 x[0] = MFMA32(a0, qv, x[0]); x[1] = MFMA32(a1, qv, x[1]);
;             }
;             float mx = x[0][0];
; #pragma unroll
;             for (int i = 1; i < 16; ++i) mx = fmaxf(mx, x[0][i]);
; #pragma unroll
;             for (int i = 0; i < 16; ++i) mx = fmaxf(mx, x[1][i]);
;             mx = fmaxf(mx, shx(mx, lane, 32));
;             if (__builtin_amdgcn_ballot_w64(mx > m_[s] + 8.f) != 0) {
;                 const float mn = fmaxf(m_[s], mx);
;                 const float al = __builtin_amdgcn_exp2f(m_[s] - mn);
;                 m_[s] = mn;
;                 l_[s] *= al;
; #pragma unroll
;                 for (int d = 0; d < 2; ++d)
; #pragma unroll
;                     for (int i = 0; i < 16; ++i) O[s][d][i] *= al;
;             }
.Lat32_loop:
	s_and_b32 s9, s8, 1
	s_mul_i32 s10, s9, 0x2400
	s_mul_i32 s11, s9, 0x2200
	v_add_u32_e32 v206, s10, v149
	v_add_u32_e32 v207, s11, v172
	v_add_u32_e32 v208, 0x5800, v207
	v_add_u32_e32 v207, 0x4800, v207
	s_waitcnt lgkmcnt(0)
	v_mfma_f32_32x32x16_bf16 v[80:95], v[128:131], v[216:219], v[174:189]
	v_mfma_f32_32x32x16_bf16 v[80:95], v[136:139], v[220:223], v[80:95]
	v_mfma_f32_32x32x16_bf16 v[64:79], v[132:135], v[216:219], v[174:189]
	v_mfma_f32_32x32x16_bf16 v[64:79], v[140:143], v[220:223], v[64:79]
	ds_read2_b64 v[96:99], v207 offset0:0 offset1:2
	ds_read2_b64 v[112:115], v208 offset0:32 offset1:34
	ds_read2_b64 v[100:103], v207 offset0:4 offset1:6
	ds_read2_b64 v[116:119], v208 offset0:36 offset1:38
	ds_read2_b64 v[104:107], v207 offset0:8 offset1:10
	ds_read2_b64 v[120:123], v208 offset0:40 offset1:42
	ds_read2_b64 v[108:111], v207 offset0:12 offset1:14
	ds_read2_b64 v[124:127], v208 offset0:44 offset1:46
	ds_read_b128 v[128:131], v206 offset:64
	ds_read_b128 v[132:135], v206 offset:4672
	ds_read_b128 v[136:139], v206 offset:96
	ds_read_b128 v[140:143], v206 offset:4704
	v_max3_f32 v209, v80, v81, v82
	v_max3_f32 v209, v209, v83, v84
	v_max3_f32 v209, v209, v85, v86
	v_max3_f32 v209, v209, v87, v88
	v_max3_f32 v209, v209, v89, v90
	v_max3_f32 v209, v209, v91, v92
	v_max3_f32 v209, v209, v93, v94
	v_max3_f32 v209, v209, v95, v64
	v_max3_f32 v209, v209, v65, v66
	v_max3_f32 v209, v209, v67, v68
	v_max3_f32 v209, v209, v69, v70
	v_max3_f32 v209, v209, v71, v72
	v_max3_f32 v209, v209, v73, v74
	v_max3_f32 v209, v209, v75, v76
	v_max3_f32 v209, v209, v77, v78
	v_max_f32_e32 v209, v209, v79
	v_mov_b32_e32 v210, v209
	s_nop 1
	v_permlane32_swap_b32_e32 v210, v209
	s_nop 0
	v_max_f32_e32 v209, v209, v210
	v_cmp_lt_f32_e32 vcc, 0x41000000, v209
	s_cbranch_vccz .Lat32_nors0
	v_max_f32_e32 v213, 0, v209
	v_mov_b32_e32 v212, v213
	v_sub_f32_e32 v210, 0, v213
	v_exp_f32_e32 v210, v210
	v_add_f32_e32 v152, v152, v213
	v_mov_b32_e32 v153, v152
	v_mul_f32_e32 v151, v151, v210
	v_pk_add_f32 v[80:81], v[80:81], v[212:213] neg_lo:[0,1] neg_hi:[0,1]
	v_pk_add_f32 v[82:83], v[82:83], v[212:213] neg_lo:[0,1] neg_hi:[0,1]
	v_pk_add_f32 v[84:85], v[84:85], v[212:213] neg_lo:[0,1] neg_hi:[0,1]
	v_pk_add_f32 v[86:87], v[86:87], v[212:213] neg_lo:[0,1] neg_hi:[0,1]
	v_pk_add_f32 v[88:89], v[88:89], v[212:213] neg_lo:[0,1] neg_hi:[0,1]
	v_pk_add_f32 v[90:91], v[90:91], v[212:213] neg_lo:[0,1] neg_hi:[0,1]
	v_pk_add_f32 v[92:93], v[92:93], v[212:213] neg_lo:[0,1] neg_hi:[0,1]
	v_pk_add_f32 v[94:95], v[94:95], v[212:213] neg_lo:[0,1] neg_hi:[0,1]
	v_pk_add_f32 v[64:65], v[64:65], v[212:213] neg_lo:[0,1] neg_hi:[0,1]
	v_pk_add_f32 v[66:67], v[66:67], v[212:213] neg_lo:[0,1] neg_hi:[0,1]
	v_pk_add_f32 v[68:69], v[68:69], v[212:213] neg_lo:[0,1] neg_hi:[0,1]
	v_pk_add_f32 v[70:71], v[70:71], v[212:213] neg_lo:[0,1] neg_hi:[0,1]
	v_pk_add_f32 v[72:73], v[72:73], v[212:213] neg_lo:[0,1] neg_hi:[0,1]
	v_pk_add_f32 v[74:75], v[74:75], v[212:213] neg_lo:[0,1] neg_hi:[0,1]
	v_pk_add_f32 v[76:77], v[76:77], v[212:213] neg_lo:[0,1] neg_hi:[0,1]
	v_pk_add_f32 v[78:79], v[78:79], v[212:213] neg_lo:[0,1] neg_hi:[0,1]
	v_sub_f32_e32 v174, 0, v152
	v_sub_f32_e32 v175, 0, v152
	v_sub_f32_e32 v176, 0, v152
	v_sub_f32_e32 v177, 0, v152
	v_sub_f32_e32 v178, 0, v152
	v_sub_f32_e32 v179, 0, v152
	v_sub_f32_e32 v180, 0, v152
	v_sub_f32_e32 v181, 0, v152
	v_sub_f32_e32 v182, 0, v152
	v_sub_f32_e32 v183, 0, v152
	v_sub_f32_e32 v184, 0, v152
	v_sub_f32_e32 v185, 0, v152
	v_sub_f32_e32 v186, 0, v152
	v_sub_f32_e32 v187, 0, v152
	v_sub_f32_e32 v188, 0, v152
	v_sub_f32_e32 v189, 0, v152
	v_pk_mul_f32 v[32:33], v[32:33], v[210:211] op_sel_hi:[1,0]
	v_pk_mul_f32 v[34:35], v[34:35], v[210:211] op_sel_hi:[1,0]
	v_pk_mul_f32 v[36:37], v[36:37], v[210:211] op_sel_hi:[1,0]
	v_pk_mul_f32 v[38:39], v[38:39], v[210:211] op_sel_hi:[1,0]
	v_pk_mul_f32 v[40:41], v[40:41], v[210:211] op_sel_hi:[1,0]
	v_pk_mul_f32 v[42:43], v[42:43], v[210:211] op_sel_hi:[1,0]
	v_pk_mul_f32 v[44:45], v[44:45], v[210:211] op_sel_hi:[1,0]
	v_pk_mul_f32 v[46:47], v[46:47], v[210:211] op_sel_hi:[1,0]
	v_pk_mul_f32 v[0:1], v[0:1], v[210:211] op_sel_hi:[1,0]
	v_pk_mul_f32 v[2:3], v[2:3], v[210:211] op_sel_hi:[1,0]
	v_pk_mul_f32 v[4:5], v[4:5], v[210:211] op_sel_hi:[1,0]
	v_pk_mul_f32 v[6:7], v[6:7], v[210:211] op_sel_hi:[1,0]
	v_pk_mul_f32 v[8:9], v[8:9], v[210:211] op_sel_hi:[1,0]
	v_pk_mul_f32 v[10:11], v[10:11], v[210:211] op_sel_hi:[1,0]
	v_pk_mul_f32 v[12:13], v[12:13], v[210:211] op_sel_hi:[1,0]
	v_pk_mul_f32 v[14:15], v[14:15], v[210:211] op_sel_hi:[1,0]
; #define MFMA32(a, b, c) __builtin_amdgcn_mfma_f32_32x32x16_bf16((a), (b), (c), 0, 0, 0)
; DI unsigned pk_bf16(float a, float b) { f32x2 v = {a, b}; bf16v2 r = __builtin_convertvector(v, bf16v2); return __builtin_bit_cast(unsigned, r); }
; template <int DK>
; DI void attn_item(const Params& p, int layer, int b, int hd, int qt, int ctxq, char* smem) {
;     ...
;             const f32x2 mref = {m_[s], m_[s]};
;             float ps = 0.f;
; #pragma unroll
;             for (int kb = 0; kb < 2; ++kb)
; #pragma unroll
;                 for (int i2 = 0; i2 < 8; ++i2) {
;                     f32x2 t = {x[kb][2 * i2], x[kb][2 * i2 + 1]};
;                     asm("v_pk_add_f32 %0, %1, %2 neg_lo:[0,1] neg_hi:[0,1]" : "=v"(t) : "v"(t), "v"(mref));
;                     const float e0 = __builtin_amdgcn_exp2f(t.x), e1 = __builtin_amdgcn_exp2f(t.y);
;                     x[kb][2 * i2] = e0; x[kb][2 * i2 + 1] = e1; ps += e0 + e1;
;                 }
;             l_[s] += ps;
; #pragma unroll
;             for (int kb = 0; kb < 2; ++kb)
; #pragma unroll
;                 for (int st = 0; st < 2; ++st) {
;                     u32x4 w;
;                     w.x = pk_bf16(x[kb][8 * st], x[kb][8 * st + 1]); w.y = pk_bf16(x[kb][8 * st + 2], x[kb][8 * st + 3]);
;                     w.z = pk_bf16(x[kb][8 * st + 4], x[kb][8 * st + 5]); w.w = pk_bf16(x[kb][8 * st + 6], x[kb][8 * st + 7]);
;                     const bf16x8 pfr = __builtin_bit_cast(bf16x8, w);
; #pragma unroll
;                     for (int d = 0; d < 2; ++d) {
;                         const bf16_t* vp = vb_ + (32 * d + r) * 68 + 32 * kb + 16 * st + 4 * h;
;                         const s16x4 lo = *(const s16x4*)vp, hi = *(const s16x4*)(vp + 8);
;                         const bf16x8 vf = __builtin_shufflevector(lo, hi, 0, 1, 2, 3, 4, 5, 6, 7);
;                         O[s][d] = MFMA32(vf, pfr, O[s][d]);
;                     }
;                 }
;         }
;         if (kt + 1 < nkt) {
;             bf16_t* wk = sK + (cur ^ 1) * 64 * 72; bf16_t* wv = sV + (cur ^ 1) * 64 * 68;
; #pragma unroll
;             for (int i = 0; i < 2; ++i) {
;                 *(u32x4*)(wk + (srow + 32 * i) * 72 + sc8) = rk[i];
;                 *(u32x2*)(wv + (srow + 32 * i) * 68 + sc8) = (u32x2){rv[i].x, rv[i].y}; *(u32x2*)(wv + (srow + 32 * i) * 68 + sc8 + 4) = (u32x2){rv[i].z, rv[i].w};
;             }
;         }
.Lat32_nors0:
	v_exp_f32_e32 v80, v80
	v_exp_f32_e32 v81, v81
	v_exp_f32_e32 v82, v82
	v_exp_f32_e32 v83, v83
	v_exp_f32_e32 v84, v84
	v_exp_f32_e32 v85, v85
	v_exp_f32_e32 v86, v86
	v_exp_f32_e32 v87, v87
	v_add_f32_e32 v211, v80, v82
	v_add_f32_e32 v212, v81, v83
	v_add_f32_e32 v211, v211, v84
	v_add_f32_e32 v212, v212, v85
	v_add_f32_e32 v211, v211, v86
	v_add_f32_e32 v212, v212, v87
	v_cvt_pk_bf16_f32 v80, v80, v81
	v_cvt_pk_bf16_f32 v81, v82, v83
	v_cvt_pk_bf16_f32 v82, v84, v85
	v_cvt_pk_bf16_f32 v83, v86, v87
	s_waitcnt lgkmcnt(0)
	s_nop 0
	v_mfma_f32_32x32x16_bf16 v[32:47], v[96:99], v[80:83], v[32:47]
	v_mfma_f32_32x32x16_bf16 v[0:15], v[112:115], v[80:83], v[0:15]
	v_exp_f32_e32 v88, v88
	v_exp_f32_e32 v89, v89
	v_exp_f32_e32 v90, v90
	v_exp_f32_e32 v91, v91
	v_exp_f32_e32 v92, v92
	v_exp_f32_e32 v93, v93
	v_exp_f32_e32 v94, v94
	v_exp_f32_e32 v95, v95
	v_add_f32_e32 v211, v211, v88
	v_add_f32_e32 v212, v212, v89
	v_add_f32_e32 v211, v211, v90
	v_add_f32_e32 v212, v212, v91
	v_add_f32_e32 v211, v211, v92
	v_add_f32_e32 v212, v212, v93
	v_add_f32_e32 v211, v211, v94
	v_add_f32_e32 v212, v212, v95
	v_cvt_pk_bf16_f32 v88, v88, v89
	v_cvt_pk_bf16_f32 v89, v90, v91
	v_cvt_pk_bf16_f32 v90, v92, v93
	v_cvt_pk_bf16_f32 v91, v94, v95
	s_nop 1
	v_mfma_f32_32x32x16_bf16 v[32:47], v[100:103], v[88:91], v[32:47]
	v_mfma_f32_32x32x16_bf16 v[0:15], v[116:119], v[88:91], v[0:15]
	v_mfma_f32_32x32x16_bf16 v[80:95], v[128:131], v[224:227], 0
	v_mfma_f32_32x32x16_bf16 v[80:95], v[136:139], v[240:243], v[80:95]
	v_exp_f32_e32 v64, v64
	v_exp_f32_e32 v65, v65
	v_exp_f32_e32 v66, v66
	v_exp_f32_e32 v67, v67
	v_exp_f32_e32 v68, v68
	v_exp_f32_e32 v69, v69
	v_exp_f32_e32 v70, v70
	v_exp_f32_e32 v71, v71
	v_add_f32_e32 v211, v211, v64
	v_add_f32_e32 v212, v212, v65
	v_add_f32_e32 v211, v211, v66
	v_add_f32_e32 v212, v212, v67
	v_add_f32_e32 v211, v211, v68
	v_add_f32_e32 v212, v212, v69
	v_add_f32_e32 v211, v211, v70
	v_add_f32_e32 v212, v212, v71
	v_cvt_pk_bf16_f32 v64, v64, v65
	v_cvt_pk_bf16_f32 v65, v66, v67
	v_cvt_pk_bf16_f32 v66, v68, v69
	v_cvt_pk_bf16_f32 v67, v70, v71
	s_nop 1
	v_mfma_f32_32x32x16_bf16 v[32:47], v[104:107], v[64:67], v[32:47]
	v_mfma_f32_32x32x16_bf16 v[0:15], v[120:123], v[64:67], v[0:15]
	v_exp_f32_e32 v72, v72
	v_exp_f32_e32 v73, v73
	v_exp_f32_e32 v74, v74
	v_exp_f32_e32 v75, v75
	v_exp_f32_e32 v76, v76
	v_exp_f32_e32 v77, v77
	v_exp_f32_e32 v78, v78
	v_exp_f32_e32 v79, v79
	v_add_f32_e32 v211, v211, v72
	v_add_f32_e32 v212, v212, v73
	v_add_f32_e32 v211, v211, v74
	v_add_f32_e32 v212, v212, v75
	v_add_f32_e32 v211, v211, v76
	v_add_f32_e32 v212, v212, v77
	v_add_f32_e32 v211, v211, v78
	v_add_f32_e32 v212, v212, v79
	v_cvt_pk_bf16_f32 v72, v72, v73
	v_cvt_pk_bf16_f32 v73, v74, v75
	v_cvt_pk_bf16_f32 v74, v76, v77
	v_cvt_pk_bf16_f32 v75, v78, v79
	v_add_f32_e32 v211, v211, v212
	v_add_f32_e32 v151, v151, v211
	v_mfma_f32_32x32x16_bf16 v[32:47], v[108:111], v[72:75], v[32:47]
	v_mfma_f32_32x32x16_bf16 v[0:15], v[124:127], v[72:75], v[0:15]
	v_mfma_f32_32x32x16_bf16 v[64:79], v[132:135], v[224:227], 0
	v_mfma_f32_32x32x16_bf16 v[64:79], v[140:143], v[240:243], v[64:79]
	s_xor_b32 s9, s9, 1
	s_mul_i32 s10, s9, 0x2400
	s_mul_i32 s11, s9, 0x2200
	v_add_u32_e32 v214, s10, v148
	v_add_u32_e32 v215, s11, v150
	v_add_u32_e32 v213, 0x5900, v215
	v_add_u32_e32 v215, 0x4800, v215
	v_add_u32_e32 v206, s10, v149
	s_waitcnt vmcnt(0)
	ds_write_b128 v214, v[190:193]
	ds_write_b128 v214, v[194:197] offset:4608
	ds_write2_b64 v215, v[198:199], v[200:201] offset1:1
	ds_write2_b64 v213, v[202:203], v[204:205] offset1:1
	s_cmp_lt_u32 s8, 0x82
	s_cbranch_scc0 .Lat32_skipld
	s_mov_b64 s[10:11], 0x80
	v_lshl_add_u64 v[244:245], v[244:245], 0, s[10:11]
	v_lshl_add_u64 v[246:247], v[246:247], 0, s[10:11]
	s_mov_b64 s[10:11], 0x2000
	v_lshl_add_u64 v[248:249], v[248:249], 0, s[10:11]
	global_load_dwordx4 v[190:193], v[248:249], off offset:-4096
	global_load_dwordx4 v[194:197], v[248:249], off
	global_load_dwordx4 v[198:201], v[244:245], off offset:128
	global_load_dwordx4 v[202:205], v[246:247], off offset:128
